# diff attention: -reference C tuple rebuilt in the previous step PV shadow from a persistent pair; per-step zero test, branch and fill removed from the step head
# speedup vs baseline: 1.0188x; 1.0009x over previous
; #define LAS __attribute__((address_space(3)))
; #define ATT_LOADK(t) do { \
;         int kr_ = kv_lo + (t) * 64 + lane; if constexpr (DIL) kr_ = kr_ < 0 ? 0 : (kr_ >= nseq ? nseq - 1 : kr_); \
;         sk0 = *(const u32x4*)(K0 + (size_t)kr_ * (size_t)(SK0 * dl) + wid * 8); \
;         if constexpr (DQK == 96) { if (wid < 4) sk1 = *(const u32x4*)(K1 + (size_t)kr_ * (size_t)(SK1 * dl) + wid * 8); } \
;     } while (0)
; #define ATT_STOREK(b) do { LAS unsigned char* kb_ = lds + KB0 + (b) * KBSZ; \
;         *(LAS u32x4*)(kb_ + wid * 1024 + lane * 16) = sk0; \
;         if constexpr (DQK == 96) { if (wid < 4) *(LAS u32x4*)(kb_ + (8 + wid) * 1024 + lane * 16) = sk1; } \
;     } while (0)
; template <int DQK, int DV, bool DIL, int dl, int SQ0, int SQ1, int SK0, int SK1, int SV, int SO> ...
;     ...
;     const int lane = tid & 63, r32 = lane & 31, hi = lane >> 5; const int wid = __builtin_amdgcn_readfirstlane(tid >> 6);
;     LAS float* wsf = (LAS float*)(lds + WSF_OFF) + wid * 64;
;     const int qrow = q0 + wid * 32 + r32;
;     bf16x8 qf[ND0];
; #pragma unroll
;     for (int d0 = 0; d0 < 4; ++d0) qf[d0] = *(const bf16x8*)(Q0 + (size_t)qrow * (size_t)(SQ0 * dl) + d0 * 16 + hi * 8);
;     if constexpr (DQK == 96) {
; #pragma unroll
;         for (int d0 = 4; d0 < 6; ++d0) qf[d0] = *(const bf16x8*)(Q1 + (size_t)qrow * (size_t)(SQ1 * dl) + (d0 - 4) * 16 + hi * 8);
;     }
;     f32x16 o[NDB];
; #pragma unroll
;     for (int i = 0; i < NDB; ++i) o[i] = (f32x16){0.f, 0.f, 0.f, 0.f, 0.f, 0.f, 0.f, 0.f, 0.f, 0.f, 0.f, 0.f, 0.f, 0.f, 0.f, 0.f};
;     const f32x16 zero16 = (f32x16){0.f, 0.f, 0.f, 0.f, 0.f, 0.f, 0.f, 0.f, 0.f, 0.f, 0.f, 0.f, 0.f, 0.f, 0.f, 0.f};
;     f32x16 negm = zero16;
;     float mrow = 0.f; f32x2 lacc = (f32x2){0.f, 0.f};
;     ...
;     ATT_LOADK(0); ATT_STOREK(0); ATT_LOADK(1); ATT_LOADV(0);
;     __syncthreads();
;     ATT_STOREK(1); ATT_STOREV(0); ATT_LOADK(2); ATT_LOADV(1);
;     if (ATT_NEED(0)) { const LAS unsigned char* kb = lds + KB0 + hi * 1024 + r32 * 16;
; #pragma unroll
;         for (int d0 = 0; d0 < ND0; ++d0) { bf16x8 k0_, k1_; ATT_KRD(k0_, k1_, kb, d0);
;             pa0 = __builtin_amdgcn_mfma_f32_32x32x16_bf16(k0_, qf[d0], d0 == 0 ? zero16 : pa0, 0, 0, 0);
;             pa1 = __builtin_amdgcn_mfma_f32_32x32x16_bf16(k1_, qf[d0], d0 == 0 ? zero16 : pa1, 0, 0, 0); }
.LBB0_227:
	s_ashr_i32 s8, s75, 8
	s_bfe_u32 s11, s75, 0x30005
	s_lshl_b32 s0, s75, 2
	s_ashr_i32 s9, s8, 31
	s_lshl_b32 s78, s11, 7
	s_and_b32 s77, s0, 0x300
	s_lshl_b64 s[12:13], s[8:9], 27
	s_add_u32 s0, s15, s12
	s_addc_u32 s1, s34, s13
	s_add_u32 s36, s0, s78
	s_addc_u32 s37, s1, 0
	s_and_b32 s10, s78, 0x300
	s_add_u32 s38, s0, s10
	v_readfirstlane_b32 s24, v249
	s_addc_u32 s39, s1, 0
	s_lshl_b32 s0, s75, 8
	s_ashr_i32 s40, s24, 6
	s_and_b32 s10, s0, 0x1f00
	s_lshl_b32 s0, s40, 3
	s_ashr_i32 s1, s0, 31
	s_lshl_b64 s[60:61], s[0:1], 1
	s_lshl_b32 s0, s40, 4
	s_and_b32 s0, s0, 48
	v_or_b32_e32 v0, s0, v197
	v_lshlrev_b32_e32 v0, 14, v0
	s_ashr_i32 s1, s24, 3
	v_mov_b32_e32 v217, v1
	v_lshl_add_u64 v[10:11], s[38:39], 0, v[0:1]
	s_and_b32 s38, s1, 0xffffffe0
	v_lshl_add_u64 v[2:3], s[36:37], 0, v[216:217]
	s_ashr_i32 s39, s38, 31
	s_waitcnt vmcnt(3)
	v_lshl_add_u64 v[18:19], v[2:3], 0, s[60:61]
	s_mov_b32 s48, 0x100000
	s_lshl_b64 s[86:87], s[38:39], 1
	v_add_co_u32_e32 v6, vcc, s48, v18
	v_lshl_add_u64 v[10:11], v[10:11], 0, s[86:87]
	v_mov_b32_e32 v207, v1
	v_addc_co_u32_e32 v7, vcc, 0, v19, vcc
	v_lshl_add_u64 v[20:21], v[10:11], 0, v[206:207]
	global_load_dwordx4 v[2:5], v[18:19], off offset:1024
	s_nop 0
	global_load_dwordx4 v[6:9], v[6:7], off offset:1024
	s_nop 0
	global_load_dwordx4 v[10:13], v[20:21], off offset:2048
	global_load_dwordx4 v[14:17], v[20:21], off offset:2176
	s_lshl_b32 s1, s40, 5
	s_add_i32 s10, s1, s10
	s_waitcnt vmcnt(6)
	v_or_b32_e32 v22, s10, v200
	v_ashrrev_i32_e32 v23, 31, v22
	v_lshlrev_b64 v[22:23], 14, v[22:23]
	v_lshlrev_b32_e32 v0, 3, v239
	v_lshl_add_u64 v[22:23], s[36:37], 0, v[22:23]
	v_lshlrev_b32_e32 v208, 1, v0
	v_mov_b32_e32 v209, v1
	v_lshl_add_u64 v[22:23], v[22:23], 0, v[208:209]
	global_load_dwordx4 v[158:161], v[22:23], off
	global_load_dwordx4 v[154:157], v[22:23], off offset:32
	global_load_dwordx4 v[150:153], v[22:23], off offset:64
	global_load_dwordx4 v[146:149], v[22:23], off offset:96
	s_lshl_b32 s1, s40, 10
	v_add_u32_e32 v217, s1, v250
	s_mov_b32 s1, 0x200000
	s_mov_b64 s[46:47], 0x100800
	s_mov_b32 s36, 0
	s_mov_b32 s37, s36
	s_mov_b32 s38, s36
	s_mov_b32 s39, s36
	s_mov_b32 s40, s36
	s_mov_b32 s41, s36
	s_mov_b32 s42, s36
	s_mov_b32 s43, s36
	s_mov_b32 s44, s36
	s_mov_b32 s45, s36
	s_mov_b32 s49, s36
	s_mov_b32 s50, s36
	s_mov_b32 s51, s36
	v_add_lshl_u32 v0, v240, s0, 14
	v_mov_b32_e32 v236, 0
	v_mov_b32_e32 v82, 0
	v_mov_b32_e32 v83, v236
	v_mov_b32_e32 v84, v236
	v_mov_b32_e32 v85, v236
	v_mov_b32_e32 v86, v236
	v_mov_b32_e32 v87, v236
	v_mov_b32_e32 v88, v236
	v_mov_b32_e32 v89, v236
	v_mov_b32_e32 v90, v236
	v_mov_b32_e32 v91, v236
	v_mov_b32_e32 v92, v236
	v_mov_b32_e32 v93, v236
	v_mov_b32_e32 v94, v236
	v_mov_b32_e32 v95, v236
	v_mov_b32_e32 v96, v236
	v_mov_b32_e32 v97, v236
	s_waitcnt vmcnt(7)
	ds_write_b128 v217, v[2:5]
	s_waitcnt lgkmcnt(0)
	s_barrier
	s_waitcnt vmcnt(6)
	ds_write_b128 v217, v[6:9] offset:12288
	s_waitcnt vmcnt(5)
	ds_write_b128 v217, v[10:13] offset:24576
	s_waitcnt vmcnt(4)
	ds_write_b128 v217, v[14:17] offset:32768
	ds_read_b128 v[2:5], v254
	ds_read_b128 v[6:9], v254 offset:512
	s_waitcnt vmcnt(3) lgkmcnt(1)
	v_mfma_f32_32x32x16_bf16 v[98:113], v[2:5], v[158:161], 0
	ds_read_b128 v[2:5], v254 offset:2048
	v_add_co_u32_e32 v10, vcc, s1, v18
	v_lshl_add_u64 v[12:13], v[20:21], 0, s[46:47]
	s_nop 0
	v_addc_co_u32_e32 v11, vcc, 0, v19, vcc
	v_add_co_u32_e32 v14, vcc, s48, v20
	s_waitcnt lgkmcnt(1)
	v_mfma_f32_32x32x16_bf16 v[66:81], v[6:9], v[158:161], 0
	v_addc_co_u32_e32 v15, vcc, 0, v21, vcc
	ds_read_b128 v[6:9], v254 offset:2560
	s_and_b32 s1, s24, 0x3fffffc0
	s_lshl_b32 s1, s1, 2
	s_mov_b32 s46, s36
	s_mov_b32 s47, s36
	s_waitcnt vmcnt(2) lgkmcnt(1)
	v_mfma_f32_32x32x16_bf16 v[98:113], v[2:5], v[154:157], v[98:113]
	ds_read_b128 v[2:5], v254 offset:4096
	global_load_dwordx4 v[166:169], v[14:15], off offset:2048
	global_load_dwordx4 v[162:165], v[10:11], off offset:1024
	global_load_dwordx4 v[170:173], v[12:13], off offset:128
	ds_read_b128 v[18:21], v254 offset:4608
	ds_read_b128 v[22:25], v254 offset:6144
	s_mov_b32 s48, s36
	s_add_i32 s1, s1, 0
	v_lshl_add_u32 v209, v200, 2, s1
	s_waitcnt lgkmcnt(3)
	v_mfma_f32_32x32x16_bf16 v[66:81], v[6:9], v[154:157], v[66:81]
	v_lshl_add_u32 v207, v253, 2, s1
	s_waitcnt vmcnt(4) lgkmcnt(2)
	v_mfma_f32_32x32x16_bf16 v[98:113], v[2:5], v[150:153], v[98:113]
	v_mov_b64_e32 v[2:3], s[36:37]
	v_mov_b64_e32 v[4:5], s[38:39]
	v_mov_b64_e32 v[6:7], s[40:41]
	v_mov_b64_e32 v[8:9], s[42:43]
	v_mov_b64_e32 v[10:11], s[44:45]
	v_mov_b64_e32 v[12:13], s[46:47]
	v_mov_b64_e32 v[14:15], s[48:49]
	s_waitcnt lgkmcnt(1)
	v_mfma_f32_32x32x16_bf16 v[66:81], v[18:21], v[150:153], v[66:81]
	ds_read_b128 v[18:21], v254 offset:6656
	v_mov_b64_e32 v[16:17], s[50:51]
	s_add_u32 s38, s78, s60
	s_addc_u32 s39, 0, s61
	v_lshl_add_u64 v[218:219], v[212:213], 0, s[38:39]
	s_add_u32 s38, s77, s86
	s_addc_u32 s39, 0, s87
	s_waitcnt vmcnt(3) lgkmcnt(1)
	v_mfma_f32_32x32x16_bf16 v[98:113], v[22:25], v[146:149], v[98:113]
	v_lshl_add_u64 v[22:23], s[38:39], 0, v[0:1]
	v_lshl_add_u64 v[220:221], v[214:215], 0, v[22:23]
	v_mov_b64_e32 v[48:49], v[16:17]
	v_mov_b64_e32 v[64:65], v[16:17]
	s_mov_b64 s[42:43], 0x200000
	v_mov_b64_e32 v[46:47], v[14:15]
	v_mov_b64_e32 v[44:45], v[12:13]
	s_waitcnt lgkmcnt(0)
; __device__ __forceinline__ float max3f(float a, float b, float c) { return __builtin_fmaxf(__builtin_fmaxf(a, b), c); }
; template <int DQK, int DV, bool DIL, int dl, int SQ0, int SQ1, int SK0, int SK1, int SV, int SO> ...
;     ...
;         float a_ = -1e30f, b_ = -1e30f;
; #pragma unroll
;         for (int i = 0; i < 8; ++i) { a_ = max3f(a_, pa0[2 * i], pa0[2 * i + 1]); b_ = max3f(b_, pa1[2 * i], pa1[2 * i + 1]); }
;         mxa = __builtin_fmaxf(a_, b_);
;     }
;     __syncthreads();
	v_mfma_f32_32x32x16_bf16 v[66:81], v[18:21], v[146:149], v[66:81]
	s_nop 2
	v_max_f32_e32 v0, v98, v98
	v_max_f32_e32 v0, 0xf149f2ca, v0
	v_max3_f32 v0, v0, v99, v100
	v_max3_f32 v0, v0, v101, v102
	v_max3_f32 v0, v0, v103, v104
	v_max3_f32 v0, v0, v105, v106
	v_max3_f32 v0, v0, v107, v108
	s_nop 1
	v_max3_f32 v18, v66, s25, v67
	v_max3_f32 v18, v18, v68, v69
	v_max3_f32 v18, v18, v70, v71
	v_max3_f32 v18, v18, v72, v73
	v_max3_f32 v18, v18, v74, v75
	v_max3_f32 v18, v18, v76, v77
	v_max3_f32 v18, v18, v78, v79
	v_max3_f32 v0, v0, v109, v110
	v_max3_f32 v18, v18, v80, v81
	v_max3_f32 v0, v0, v111, v112
	v_max3_f32 v114, v0, v113, v18
	v_add_lshl_u32 v0, v252, s0, 14
	v_lshl_add_u64 v[18:19], s[38:39], 0, v[0:1]
	v_lshl_add_u64 v[222:223], v[214:215], 0, v[18:19]
	v_mov_b32_e32 v0, v1
	v_mov_b64_e32 v[32:33], v[16:17]
	v_mov_b64_e32 v[30:31], v[14:15]
	v_mov_b64_e32 v[28:29], v[12:13]
	v_mov_b64_e32 v[26:27], v[10:11]
	v_mov_b64_e32 v[24:25], v[8:9]
	v_mov_b64_e32 v[22:23], v[6:7]
	v_mov_b64_e32 v[20:21], v[4:5]
	v_mov_b64_e32 v[18:19], v[2:3]
	v_mov_b64_e32 v[42:43], v[10:11]
	v_mov_b64_e32 v[40:41], v[8:9]
	v_mov_b64_e32 v[38:39], v[6:7]
	v_mov_b64_e32 v[36:37], v[4:5]
	v_mov_b64_e32 v[34:35], v[2:3]
	v_mov_b64_e32 v[62:63], v[14:15]
	v_mov_b64_e32 v[60:61], v[12:13]
	v_mov_b64_e32 v[58:59], v[10:11]
	v_mov_b64_e32 v[56:57], v[8:9]
	v_mov_b64_e32 v[54:55], v[6:7]
	v_mov_b64_e32 v[52:53], v[4:5]
	v_mov_b64_e32 v[50:51], v[2:3]
	v_mov_b64_e32 v[224:225], v[0:1]
	v_xor_b32_e32 v228, 0x80000000, v236
	v_mov_b32_e32 v229, v228
	v_mov_b64_e32 v[130:131], v[228:229]
	v_mov_b64_e32 v[132:133], v[228:229]
	v_mov_b64_e32 v[134:135], v[228:229]
	v_mov_b64_e32 v[136:137], v[228:229]
	v_mov_b64_e32 v[138:139], v[228:229]
	v_mov_b64_e32 v[140:141], v[228:229]
	v_mov_b64_e32 v[142:143], v[228:229]
	v_mov_b64_e32 v[144:145], v[228:229]
	s_barrier
	s_branch .LBB0_229
.LBB0_228:
	v_exp_f32_e32 v116, v116
	v_exp_f32_e32 v117, v117
	v_add_f32_e32 v224, v224, v116
	v_cvt_pk_bf16_f32 v175, v116, v117
	v_add_f32_e32 v225, v225, v117
	s_waitcnt lgkmcnt(4)
	v_mfma_f32_32x32x16_bf16 v[98:113], v[182:185], v[154:157], v[98:113]
	ds_read_b128 v[130:133], v254 offset:4096
	ds_read_b128 v[134:137], v254 offset:4608
	v_exp_f32_e32 v118, v118
	v_exp_f32_e32 v119, v119
	v_add_f32_e32 v224, v224, v118
	v_cvt_pk_bf16_f32 v176, v118, v119
	v_add_f32_e32 v225, v225, v119
	s_waitcnt lgkmcnt(5)
	v_mfma_f32_32x32x16_bf16 v[66:81], v[178:181], v[154:157], v[66:81]
	v_exp_f32_e32 v120, v120
	v_exp_f32_e32 v121, v121
	v_add_f32_e32 v224, v224, v120
	v_cvt_pk_bf16_f32 v177, v120, v121
	v_add_f32_e32 v225, v225, v121
	s_waitcnt lgkmcnt(1)
	v_mfma_f32_32x32x16_bf16 v[98:113], v[130:133], v[150:153], v[98:113]
	ds_read_b128 v[138:141], v254 offset:6144
	ds_read_b128 v[142:145], v254 offset:6656
	v_exp_f32_e32 v122, v122
	v_exp_f32_e32 v123, v123
	v_add_f32_e32 v224, v224, v122
	v_cvt_pk_bf16_f32 v130, v122, v123
	v_add_f32_e32 v225, v225, v123
	s_waitcnt lgkmcnt(2)
	v_mfma_f32_32x32x16_bf16 v[66:81], v[134:137], v[150:153], v[66:81]
	v_exp_f32_e32 v124, v124
	v_exp_f32_e32 v125, v125
	v_add_f32_e32 v224, v224, v124
	v_cvt_pk_bf16_f32 v131, v124, v125
	v_add_f32_e32 v225, v225, v125
	s_waitcnt lgkmcnt(1)
	v_mfma_f32_32x32x16_bf16 v[98:113], v[138:141], v[146:149], v[98:113]
	v_exp_f32_e32 v126, v126
	v_exp_f32_e32 v127, v127
	v_add_f32_e32 v224, v224, v126
	v_cvt_pk_bf16_f32 v132, v126, v127
	v_add_f32_e32 v225, v225, v127
	s_waitcnt lgkmcnt(0)
	v_mfma_f32_32x32x16_bf16 v[66:81], v[142:145], v[146:149], v[66:81]
	v_exp_f32_e32 v128, v128
	v_exp_f32_e32 v129, v129
	v_add_f32_e32 v224, v224, v128
	v_cvt_pk_bf16_f32 v133, v128, v129
	v_add_f32_e32 v225, v225, v129
	ds_read_b64_tr_b16 v[134:135], v243 offset:40960
	ds_read_b64_tr_b16 v[136:137], v243 offset:41472
	ds_read_b64_tr_b16 v[138:139], v243 offset:45056
	ds_read_b64_tr_b16 v[140:141], v243 offset:45568
	s_waitcnt lgkmcnt(2)
	v_mfma_f32_32x32x16_bf16 v[50:65], v[174:177], v[134:137], v[50:65]
	ds_read_b64_tr_b16 v[142:143], v243 offset:49152
	ds_read_b64_tr_b16 v[144:145], v243 offset:49664
	v_exp_f32_e32 v82, v82
	v_exp_f32_e32 v83, v83
	v_add_f32_e32 v224, v224, v82
	v_cvt_pk_bf16_f32 v114, v82, v83
	v_add_f32_e32 v225, v225, v83
	s_waitcnt lgkmcnt(2)
	v_mfma_f32_32x32x16_bf16 v[34:49], v[174:177], v[138:141], v[34:49]
	ds_read_b64_tr_b16 v[134:135], v243 offset:53248
	ds_read_b64_tr_b16 v[136:137], v243 offset:53760
	v_exp_f32_e32 v84, v84
	v_exp_f32_e32 v85, v85
	v_add_f32_e32 v224, v224, v84
	v_cvt_pk_bf16_f32 v115, v84, v85
	v_add_f32_e32 v225, v225, v85
	s_waitcnt lgkmcnt(2)
	v_mfma_f32_32x32x16_bf16 v[18:33], v[174:177], v[142:145], v[18:33]
	ds_read_b64_tr_b16 v[138:139], v243 offset:41984
	ds_read_b64_tr_b16 v[140:141], v243 offset:42496
	v_exp_f32_e32 v86, v86
	v_exp_f32_e32 v87, v87
	v_add_f32_e32 v224, v224, v86
	v_cvt_pk_bf16_f32 v116, v86, v87
	v_add_f32_e32 v225, v225, v87
	s_waitcnt lgkmcnt(2)
	v_mfma_f32_32x32x16_bf16 v[2:17], v[174:177], v[134:137], v[2:17]
	ds_read_b64_tr_b16 v[142:143], v243 offset:46080
	ds_read_b64_tr_b16 v[144:145], v243 offset:46592
	v_exp_f32_e32 v88, v88
	v_exp_f32_e32 v89, v89
	v_add_f32_e32 v224, v224, v88
	v_cvt_pk_bf16_f32 v117, v88, v89
	v_add_f32_e32 v225, v225, v89
	s_waitcnt lgkmcnt(2)
	v_mfma_f32_32x32x16_bf16 v[50:65], v[130:133], v[138:141], v[50:65]
	ds_read_b64_tr_b16 v[134:135], v243 offset:50176
	ds_read_b64_tr_b16 v[136:137], v243 offset:50688
	v_exp_f32_e32 v90, v90
	v_exp_f32_e32 v91, v91
	v_add_f32_e32 v224, v224, v90
	v_cvt_pk_bf16_f32 v118, v90, v91
	v_add_f32_e32 v225, v225, v91
	s_waitcnt lgkmcnt(2)
	v_mfma_f32_32x32x16_bf16 v[34:49], v[130:133], v[142:145], v[34:49]
	ds_read_b64_tr_b16 v[138:139], v243 offset:54272
	ds_read_b64_tr_b16 v[140:141], v243 offset:54784
	v_exp_f32_e32 v92, v92
	v_exp_f32_e32 v93, v93
	v_add_f32_e32 v224, v224, v92
	v_cvt_pk_bf16_f32 v119, v92, v93
	v_add_f32_e32 v225, v225, v93
	s_waitcnt lgkmcnt(2)
	v_mfma_f32_32x32x16_bf16 v[18:33], v[130:133], v[134:137], v[18:33]
	ds_read_b64_tr_b16 v[142:143], v243 offset:43008
	ds_read_b64_tr_b16 v[144:145], v243 offset:43520
	v_exp_f32_e32 v94, v94
	v_exp_f32_e32 v95, v95
	v_add_f32_e32 v224, v224, v94
	v_cvt_pk_bf16_f32 v120, v94, v95
	v_add_f32_e32 v225, v225, v95
	s_waitcnt lgkmcnt(2)
	v_mfma_f32_32x32x16_bf16 v[2:17], v[130:133], v[138:141], v[2:17]
	ds_read_b64_tr_b16 v[134:135], v243 offset:47104
	ds_read_b64_tr_b16 v[136:137], v243 offset:47616
	v_exp_f32_e32 v96, v96
	v_exp_f32_e32 v97, v97
	v_add_f32_e32 v224, v224, v96
	v_cvt_pk_bf16_f32 v121, v96, v97
	v_add_f32_e32 v225, v225, v97
	s_waitcnt lgkmcnt(2)
	v_mfma_f32_32x32x16_bf16 v[50:65], v[114:117], v[142:145], v[50:65]
	ds_read_b64_tr_b16 v[128:129], v243 offset:51200
	ds_read_b64_tr_b16 v[130:131], v243 offset:51712
	v_max_f32_e32 v0, v98, v98
	v_max_f32_e32 v0, 0xf149f2ca, v0
	v_max3_f32 v174, v66, s25, v67
	s_waitcnt lgkmcnt(2)
	v_mfma_f32_32x32x16_bf16 v[34:49], v[114:117], v[134:137], v[34:49]
	ds_read_b64_tr_b16 v[138:139], v243 offset:55296
	ds_read_b64_tr_b16 v[140:141], v243 offset:55808
	v_max3_f32 v0, v0, v99, v100
	v_max3_f32 v174, v174, v68, v69
	s_waitcnt lgkmcnt(2)
	v_mfma_f32_32x32x16_bf16 v[18:33], v[114:117], v[128:131], v[18:33]
	ds_read_b64_tr_b16 v[132:133], v243 offset:44032
	ds_read_b64_tr_b16 v[134:135], v243 offset:44544
	v_max3_f32 v0, v0, v101, v102
	v_max3_f32 v174, v174, v70, v71
	s_waitcnt lgkmcnt(2)
	v_mfma_f32_32x32x16_bf16 v[2:17], v[114:117], v[138:141], v[2:17]
	ds_read_b64_tr_b16 v[128:129], v243 offset:48128
	ds_read_b64_tr_b16 v[130:131], v243 offset:48640
	v_max3_f32 v0, v0, v103, v104
	v_max3_f32 v174, v174, v72, v73
	s_waitcnt lgkmcnt(2)
	v_mfma_f32_32x32x16_bf16 v[50:65], v[118:121], v[132:135], v[50:65]
	ds_read_b64_tr_b16 v[114:115], v243 offset:52224
	ds_read_b64_tr_b16 v[116:117], v243 offset:52736
	v_max3_f32 v0, v0, v105, v106
	v_max3_f32 v174, v174, v74, v75
	v_mov_b64_e32 v[136:137], v[228:229]
	v_mov_b64_e32 v[138:139], v[228:229]
	s_waitcnt lgkmcnt(2)
	v_mfma_f32_32x32x16_bf16 v[34:49], v[118:121], v[128:131], v[34:49]
	ds_read_b64_tr_b16 v[132:133], v243 offset:56320
	ds_read_b64_tr_b16 v[134:135], v243 offset:56832
	v_max3_f32 v0, v0, v107, v108
	v_max3_f32 v174, v174, v76, v77
	v_mov_b64_e32 v[140:141], v[228:229]
	v_mov_b64_e32 v[142:143], v[228:229]
	s_waitcnt lgkmcnt(2)
	v_mfma_f32_32x32x16_bf16 v[18:33], v[118:121], v[114:117], v[18:33]
	v_max3_f32 v0, v0, v109, v110
	v_max3_f32 v174, v174, v78, v79
	v_mov_b64_e32 v[144:145], v[228:229]
	v_mov_b64_e32 v[130:131], v[228:229]
	s_waitcnt lgkmcnt(0)
	v_mfma_f32_32x32x16_bf16 v[2:17], v[118:121], v[132:135], v[2:17]
	v_max3_f32 v0, v0, v111, v112
	v_max3_f32 v174, v174, v80, v81
	v_mov_b64_e32 v[132:133], v[228:229]
	v_mov_b64_e32 v[134:135], v[228:229]
	s_add_i32 s36, s36, 2
	v_max3_f32 v114, v0, v113, v174
	v_lshl_add_u64 v[218:219], v[218:219], 0, s[42:43]
	v_lshl_add_u64 v[220:221], v[220:221], 0, s[42:43]
	s_cmpk_gt_u32 s36, 0x7d
	v_lshl_add_u64 v[222:223], v[222:223], 0, s[42:43]
	s_barrier
	s_cbranch_scc1 .LBB0_255
.LBB0_229:
	v_cmp_lt_f32_e32 vcc, s16, v114
	s_cbranch_vccz .LBB0_233
	ds_bpermute_b32 v0, v251, v114
	s_waitcnt lgkmcnt(0)
	v_max3_f32 v114, v114, v0, 0
	v_exp_f32_e64 v0, -v114
	s_and_saveexec_b64 s[38:39], s[6:7]
	ds_write_b32 v209, v0 offset:57344
	s_or_b64 exec, exec, s[38:39]
	v_sub_f32_e32 v113, v113, v114
	v_sub_f32_e32 v112, v112, v114
	v_sub_f32_e32 v111, v111, v114
	v_sub_f32_e32 v110, v110, v114
	v_sub_f32_e32 v109, v109, v114
	v_sub_f32_e32 v108, v108, v114
	v_sub_f32_e32 v107, v107, v114
	v_sub_f32_e32 v106, v106, v114
	v_sub_f32_e32 v105, v105, v114
	v_sub_f32_e32 v104, v104, v114
	v_sub_f32_e32 v103, v103, v114
	v_sub_f32_e32 v102, v102, v114
	v_sub_f32_e32 v101, v101, v114
	v_sub_f32_e32 v100, v100, v114
	v_sub_f32_e32 v99, v99, v114
	v_sub_f32_e32 v98, v98, v114
	v_sub_f32_e32 v81, v81, v114
	v_sub_f32_e32 v80, v80, v114
	v_sub_f32_e32 v79, v79, v114
	v_sub_f32_e32 v78, v78, v114
	v_sub_f32_e32 v77, v77, v114
	v_sub_f32_e32 v76, v76, v114
	v_sub_f32_e32 v75, v75, v114
	v_sub_f32_e32 v74, v74, v114
	v_sub_f32_e32 v73, v73, v114
	v_sub_f32_e32 v72, v72, v114
	v_sub_f32_e32 v71, v71, v114
	v_sub_f32_e32 v70, v70, v114
	v_sub_f32_e32 v69, v69, v114
	v_sub_f32_e32 v68, v68, v114
	v_sub_f32_e32 v67, v67, v114
	v_sub_f32_e32 v66, v66, v114
	v_add_f32_e32 v236, v236, v114
	ds_read_b128 v[114:117], v207 offset:57344
	ds_read_b128 v[118:121], v207 offset:57376
	ds_read_b128 v[122:125], v207 offset:57408
	ds_read_b128 v[126:129], v207 offset:57440
	v_pk_mul_f32 v[224:225], v[224:225], v[0:1] op_sel_hi:[1,0]
	s_waitcnt lgkmcnt(3)
	v_pk_mul_f32 v[52:53], v[52:53], v[116:117]
	s_waitcnt lgkmcnt(2)
	v_pk_mul_f32 v[56:57], v[56:57], v[120:121]
	s_waitcnt lgkmcnt(1)
	v_pk_mul_f32 v[60:61], v[60:61], v[124:125]
	s_waitcnt lgkmcnt(0)
	v_pk_mul_f32 v[64:65], v[64:65], v[128:129]
	v_pk_mul_f32 v[62:63], v[62:63], v[126:127]
	v_pk_mul_f32 v[58:59], v[58:59], v[122:123]
	v_pk_mul_f32 v[54:55], v[54:55], v[118:119]
	v_pk_mul_f32 v[50:51], v[50:51], v[114:115]
	v_pk_mul_f32 v[48:49], v[48:49], v[128:129]
	v_pk_mul_f32 v[44:45], v[44:45], v[124:125]
	v_pk_mul_f32 v[40:41], v[40:41], v[120:121]
	v_pk_mul_f32 v[36:37], v[36:37], v[116:117]
	v_pk_mul_f32 v[46:47], v[46:47], v[126:127]
	v_pk_mul_f32 v[42:43], v[42:43], v[122:123]
	v_pk_mul_f32 v[38:39], v[38:39], v[118:119]
	v_pk_mul_f32 v[34:35], v[34:35], v[114:115]
	v_pk_mul_f32 v[32:33], v[32:33], v[128:129]
	v_pk_mul_f32 v[28:29], v[28:29], v[124:125]
	v_pk_mul_f32 v[24:25], v[24:25], v[120:121]
	v_pk_mul_f32 v[20:21], v[20:21], v[116:117]
	v_pk_mul_f32 v[30:31], v[30:31], v[126:127]
	v_pk_mul_f32 v[26:27], v[26:27], v[122:123]
	v_pk_mul_f32 v[22:23], v[22:23], v[118:119]
	v_pk_mul_f32 v[18:19], v[18:19], v[114:115]
	v_pk_mul_f32 v[16:17], v[16:17], v[128:129]
	v_pk_mul_f32 v[12:13], v[12:13], v[124:125]
	v_pk_mul_f32 v[8:9], v[8:9], v[120:121]
	v_pk_mul_f32 v[4:5], v[4:5], v[116:117]
	v_pk_mul_f32 v[14:15], v[14:15], v[126:127]
	v_pk_mul_f32 v[10:11], v[10:11], v[122:123]
	v_pk_mul_f32 v[6:7], v[6:7], v[118:119]
	v_pk_mul_f32 v[2:3], v[2:3], v[114:115]
	v_xor_b32_e32 v228, 0x80000000, v236
	v_mov_b32_e32 v229, v228
	v_mov_b64_e32 v[130:131], v[228:229]
	v_mov_b64_e32 v[132:133], v[228:229]
	v_mov_b64_e32 v[134:135], v[228:229]
	v_mov_b64_e32 v[136:137], v[228:229]
	v_mov_b64_e32 v[138:139], v[228:229]
	v_mov_b64_e32 v[140:141], v[228:229]
	v_mov_b64_e32 v[142:143], v[228:229]
	v_mov_b64_e32 v[144:145], v[228:229]
.LBB0_233:
	ds_read_b128 v[174:177], v254 offset:12288
	ds_read_b128 v[186:189], v254 offset:12800
	ds_read_b128 v[182:185], v254 offset:14336
	ds_read_b128 v[178:181], v254 offset:14848
	v_lshl_add_u64 v[226:227], v[218:219], 0, s[12:13]
	v_add_co_u32_e32 v114, vcc, 0x9700000, v226
	s_waitcnt vmcnt(1)
	ds_write_b128 v217, v[162:165]
	ds_write_b128 v217, v[166:169] offset:40960
	s_waitcnt vmcnt(0)
	ds_write_b128 v217, v[170:173] offset:49152
	v_addc_co_u32_e32 v115, vcc, 0, v227, vcc
	global_load_dwordx4 v[162:165], v[114:115], off offset:1024
	v_lshl_add_u64 v[114:115], v[222:223], 0, s[12:13]
	v_add_co_u32_e32 v114, vcc, 0x9400000, v114
	s_nop 1
	v_addc_co_u32_e32 v115, vcc, 0, v115, vcc
	global_load_dwordx4 v[170:173], v[114:115], off offset:2048
	global_load_dwordx4 v[166:169], v[114:115], off offset:2176
	v_exp_f32_e32 v98, v98
	v_exp_f32_e32 v99, v99
	s_waitcnt lgkmcnt(6)
	v_mfma_f32_32x32x16_bf16 v[114:129], v[174:177], v[158:161], v[130:145]
	v_add_f32_e32 v224, v224, v98
	v_cvt_pk_bf16_f32 v174, v98, v99
	v_add_f32_e32 v225, v225, v99
	s_waitcnt lgkmcnt(5)
	v_mfma_f32_32x32x16_bf16 v[82:97], v[186:189], v[158:161], v[130:145]
.LBB0_241:
	v_exp_f32_e32 v100, v100
	v_exp_f32_e32 v101, v101
	v_add_f32_e32 v224, v224, v100
	v_cvt_pk_bf16_f32 v175, v100, v101
	v_add_f32_e32 v225, v225, v101
	s_waitcnt lgkmcnt(4)
	v_mfma_f32_32x32x16_bf16 v[114:129], v[182:185], v[154:157], v[114:129]
	ds_read_b128 v[130:133], v254 offset:16384
	ds_read_b128 v[134:137], v254 offset:16896
	v_exp_f32_e32 v102, v102
	v_exp_f32_e32 v103, v103
	v_add_f32_e32 v224, v224, v102
	v_cvt_pk_bf16_f32 v176, v102, v103
	v_add_f32_e32 v225, v225, v103
	s_waitcnt lgkmcnt(5)
	v_mfma_f32_32x32x16_bf16 v[82:97], v[178:181], v[154:157], v[82:97]
	v_exp_f32_e32 v104, v104
	v_exp_f32_e32 v105, v105
	v_add_f32_e32 v224, v224, v104
	v_cvt_pk_bf16_f32 v177, v104, v105
	v_add_f32_e32 v225, v225, v105
	s_waitcnt lgkmcnt(1)
	v_mfma_f32_32x32x16_bf16 v[114:129], v[130:133], v[150:153], v[114:129]
	ds_read_b128 v[138:141], v254 offset:18432
	ds_read_b128 v[142:145], v254 offset:18944
	v_exp_f32_e32 v106, v106
	v_exp_f32_e32 v107, v107
	v_add_f32_e32 v224, v224, v106
	v_cvt_pk_bf16_f32 v130, v106, v107
	v_add_f32_e32 v225, v225, v107
	s_waitcnt lgkmcnt(2)
	v_mfma_f32_32x32x16_bf16 v[82:97], v[134:137], v[150:153], v[82:97]
	v_exp_f32_e32 v108, v108
	v_exp_f32_e32 v109, v109
	v_add_f32_e32 v224, v224, v108
	v_cvt_pk_bf16_f32 v131, v108, v109
	v_add_f32_e32 v225, v225, v109
	s_waitcnt lgkmcnt(1)
	v_mfma_f32_32x32x16_bf16 v[114:129], v[138:141], v[146:149], v[114:129]
	v_exp_f32_e32 v110, v110
	v_exp_f32_e32 v111, v111
	v_add_f32_e32 v224, v224, v110
	v_cvt_pk_bf16_f32 v132, v110, v111
	v_add_f32_e32 v225, v225, v111
	s_waitcnt lgkmcnt(0)
	v_mfma_f32_32x32x16_bf16 v[82:97], v[142:145], v[146:149], v[82:97]
	v_exp_f32_e32 v112, v112
	v_exp_f32_e32 v113, v113
	v_add_f32_e32 v224, v224, v112
	v_cvt_pk_bf16_f32 v133, v112, v113
	v_add_f32_e32 v225, v225, v113
	ds_read_b64_tr_b16 v[134:135], v243 offset:24576
	ds_read_b64_tr_b16 v[136:137], v243 offset:25088
	ds_read_b64_tr_b16 v[138:139], v243 offset:28672
	ds_read_b64_tr_b16 v[140:141], v243 offset:29184
	s_waitcnt lgkmcnt(2)
	v_mfma_f32_32x32x16_bf16 v[50:65], v[174:177], v[134:137], v[50:65]
	ds_read_b64_tr_b16 v[142:143], v243 offset:32768
	ds_read_b64_tr_b16 v[144:145], v243 offset:33280
	v_exp_f32_e32 v66, v66
	v_exp_f32_e32 v67, v67
	v_add_f32_e32 v224, v224, v66
	v_cvt_pk_bf16_f32 v98, v66, v67
	v_add_f32_e32 v225, v225, v67
	s_waitcnt lgkmcnt(2)
	v_mfma_f32_32x32x16_bf16 v[34:49], v[174:177], v[138:141], v[34:49]
	ds_read_b64_tr_b16 v[134:135], v243 offset:36864
	ds_read_b64_tr_b16 v[136:137], v243 offset:37376
	v_exp_f32_e32 v68, v68
	v_exp_f32_e32 v69, v69
	v_add_f32_e32 v224, v224, v68
	v_cvt_pk_bf16_f32 v99, v68, v69
	v_add_f32_e32 v225, v225, v69
	s_waitcnt lgkmcnt(2)
	v_mfma_f32_32x32x16_bf16 v[18:33], v[174:177], v[142:145], v[18:33]
	ds_read_b64_tr_b16 v[138:139], v243 offset:25600
	ds_read_b64_tr_b16 v[140:141], v243 offset:26112
	v_exp_f32_e32 v70, v70
	v_exp_f32_e32 v71, v71
	v_add_f32_e32 v224, v224, v70
	v_cvt_pk_bf16_f32 v100, v70, v71
	v_add_f32_e32 v225, v225, v71
	s_waitcnt lgkmcnt(2)
	v_mfma_f32_32x32x16_bf16 v[2:17], v[174:177], v[134:137], v[2:17]
	ds_read_b64_tr_b16 v[142:143], v243 offset:29696
	ds_read_b64_tr_b16 v[144:145], v243 offset:30208
	v_exp_f32_e32 v72, v72
	v_exp_f32_e32 v73, v73
	v_add_f32_e32 v224, v224, v72
	v_cvt_pk_bf16_f32 v101, v72, v73
	v_add_f32_e32 v225, v225, v73
	s_waitcnt lgkmcnt(2)
	v_mfma_f32_32x32x16_bf16 v[50:65], v[130:133], v[138:141], v[50:65]
	ds_read_b64_tr_b16 v[134:135], v243 offset:33792
	ds_read_b64_tr_b16 v[136:137], v243 offset:34304
	v_exp_f32_e32 v74, v74
	v_exp_f32_e32 v75, v75
	v_add_f32_e32 v224, v224, v74
	v_cvt_pk_bf16_f32 v102, v74, v75
	v_add_f32_e32 v225, v225, v75
	s_waitcnt lgkmcnt(2)
	v_mfma_f32_32x32x16_bf16 v[34:49], v[130:133], v[142:145], v[34:49]
	ds_read_b64_tr_b16 v[138:139], v243 offset:37888
	ds_read_b64_tr_b16 v[140:141], v243 offset:38400
	v_exp_f32_e32 v76, v76
	v_exp_f32_e32 v77, v77
	v_add_f32_e32 v224, v224, v76
	v_cvt_pk_bf16_f32 v103, v76, v77
	v_add_f32_e32 v225, v225, v77
	s_waitcnt lgkmcnt(2)
	v_mfma_f32_32x32x16_bf16 v[18:33], v[130:133], v[134:137], v[18:33]
	ds_read_b64_tr_b16 v[142:143], v243 offset:26624
	ds_read_b64_tr_b16 v[144:145], v243 offset:27136
	v_exp_f32_e32 v78, v78
	v_exp_f32_e32 v79, v79
	v_add_f32_e32 v224, v224, v78
	v_cvt_pk_bf16_f32 v104, v78, v79
	v_add_f32_e32 v225, v225, v79
	s_waitcnt lgkmcnt(2)
	v_mfma_f32_32x32x16_bf16 v[2:17], v[130:133], v[138:141], v[2:17]
	ds_read_b64_tr_b16 v[134:135], v243 offset:30720
	ds_read_b64_tr_b16 v[136:137], v243 offset:31232
	v_exp_f32_e32 v80, v80
	v_exp_f32_e32 v81, v81
	v_add_f32_e32 v224, v224, v80
	v_cvt_pk_bf16_f32 v105, v80, v81
	v_add_f32_e32 v225, v225, v81
	s_waitcnt lgkmcnt(2)
	v_mfma_f32_32x32x16_bf16 v[50:65], v[98:101], v[142:145], v[50:65]
	ds_read_b64_tr_b16 v[130:131], v243 offset:34816
	ds_read_b64_tr_b16 v[132:133], v243 offset:35328
	v_max_f32_e32 v0, v114, v114
	v_max_f32_e32 v0, 0xf149f2ca, v0
	v_max3_f32 v112, v82, s25, v83
	s_waitcnt lgkmcnt(2)
	v_mfma_f32_32x32x16_bf16 v[34:49], v[98:101], v[134:137], v[34:49]
	ds_read_b64_tr_b16 v[138:139], v243 offset:38912
	ds_read_b64_tr_b16 v[140:141], v243 offset:39424
	v_max3_f32 v0, v0, v115, v116
	v_max3_f32 v112, v112, v84, v85
	s_waitcnt lgkmcnt(2)
	v_mfma_f32_32x32x16_bf16 v[18:33], v[98:101], v[130:133], v[18:33]
	ds_read_b64_tr_b16 v[134:135], v243 offset:27648
	ds_read_b64_tr_b16 v[136:137], v243 offset:28160
	v_max3_f32 v0, v0, v117, v118
	v_max3_f32 v112, v112, v86, v87
	s_waitcnt lgkmcnt(2)
	v_mfma_f32_32x32x16_bf16 v[2:17], v[98:101], v[138:141], v[2:17]
	ds_read_b64_tr_b16 v[130:131], v243 offset:31744
	ds_read_b64_tr_b16 v[132:133], v243 offset:32256
	v_max3_f32 v0, v0, v119, v120
	v_max3_f32 v112, v112, v88, v89
	s_waitcnt lgkmcnt(2)
	v_mfma_f32_32x32x16_bf16 v[50:65], v[102:105], v[134:137], v[50:65]
	ds_read_b64_tr_b16 v[98:99], v243 offset:35840
	ds_read_b64_tr_b16 v[100:101], v243 offset:36352
	v_max3_f32 v0, v0, v121, v122
	v_max3_f32 v112, v112, v90, v91
	v_mov_b64_e32 v[138:139], v[228:229]
	v_mov_b64_e32 v[140:141], v[228:229]
	s_waitcnt lgkmcnt(2)
	v_mfma_f32_32x32x16_bf16 v[34:49], v[102:105], v[130:133], v[34:49]
	ds_read_b64_tr_b16 v[134:135], v243 offset:39936
	ds_read_b64_tr_b16 v[136:137], v243 offset:40448
	v_max3_f32 v0, v0, v123, v124
	v_max3_f32 v112, v112, v92, v93
	v_mov_b64_e32 v[142:143], v[228:229]
	v_mov_b64_e32 v[144:145], v[228:229]
	s_waitcnt lgkmcnt(2)
	v_mfma_f32_32x32x16_bf16 v[18:33], v[102:105], v[98:101], v[18:33]
	v_max3_f32 v0, v0, v125, v126
	v_max3_f32 v112, v112, v94, v95
	v_mov_b64_e32 v[130:131], v[228:229]
	v_mov_b64_e32 v[132:133], v[228:229]
	s_waitcnt lgkmcnt(0)
	v_mfma_f32_32x32x16_bf16 v[2:17], v[102:105], v[134:137], v[2:17]
	v_max3_f32 v0, v0, v127, v128
	v_max3_f32 v112, v112, v96, v97
	v_mov_b64_e32 v[134:135], v[228:229]
	v_mov_b64_e32 v[136:137], v[228:229]
	v_max3_f32 v0, v0, v129, v112
	v_cmp_lt_f32_e32 vcc, s16, v0
	s_barrier
	s_cbranch_vccz .LBB0_245
	ds_bpermute_b32 v98, v251, v0
	s_waitcnt lgkmcnt(0)
	v_max3_f32 v98, v0, v98, 0
	v_exp_f32_e64 v0, -v98
	s_and_saveexec_b64 s[38:39], s[6:7]
	ds_write_b32 v209, v0 offset:57344
	s_or_b64 exec, exec, s[38:39]
	v_sub_f32_e32 v129, v129, v98
	v_sub_f32_e32 v128, v128, v98
	v_sub_f32_e32 v127, v127, v98
	v_sub_f32_e32 v126, v126, v98
	v_sub_f32_e32 v125, v125, v98
	v_sub_f32_e32 v124, v124, v98
	v_sub_f32_e32 v123, v123, v98
	v_sub_f32_e32 v122, v122, v98
	v_sub_f32_e32 v121, v121, v98
	v_sub_f32_e32 v120, v120, v98
	v_sub_f32_e32 v119, v119, v98
	v_sub_f32_e32 v118, v118, v98
	v_sub_f32_e32 v117, v117, v98
	v_sub_f32_e32 v116, v116, v98
	v_sub_f32_e32 v115, v115, v98
	v_sub_f32_e32 v114, v114, v98
	v_sub_f32_e32 v82, v82, v98
	v_sub_f32_e32 v83, v83, v98
	v_sub_f32_e32 v84, v84, v98
	v_sub_f32_e32 v85, v85, v98
	v_sub_f32_e32 v86, v86, v98
	v_sub_f32_e32 v87, v87, v98
	v_sub_f32_e32 v88, v88, v98
	v_sub_f32_e32 v89, v89, v98
	v_sub_f32_e32 v90, v90, v98
	v_sub_f32_e32 v91, v91, v98
	v_sub_f32_e32 v92, v92, v98
	v_sub_f32_e32 v93, v93, v98
	v_sub_f32_e32 v94, v94, v98
	v_sub_f32_e32 v95, v95, v98
	v_sub_f32_e32 v96, v96, v98
	v_sub_f32_e32 v97, v97, v98
	v_add_f32_e32 v236, v236, v98
	ds_read_b128 v[98:101], v207 offset:57344
	ds_read_b128 v[102:105], v207 offset:57376
	ds_read_b128 v[106:109], v207 offset:57408
	ds_read_b128 v[110:113], v207 offset:57440
	v_pk_mul_f32 v[224:225], v[224:225], v[0:1] op_sel_hi:[1,0]
	s_waitcnt lgkmcnt(3)
	v_pk_mul_f32 v[52:53], v[52:53], v[100:101]
	s_waitcnt lgkmcnt(2)
	v_pk_mul_f32 v[56:57], v[56:57], v[104:105]
	s_waitcnt lgkmcnt(1)
	v_pk_mul_f32 v[60:61], v[60:61], v[108:109]
	s_waitcnt lgkmcnt(0)
	v_pk_mul_f32 v[64:65], v[64:65], v[112:113]
	v_pk_mul_f32 v[62:63], v[62:63], v[110:111]
	v_pk_mul_f32 v[58:59], v[58:59], v[106:107]
	v_pk_mul_f32 v[54:55], v[54:55], v[102:103]
	v_pk_mul_f32 v[50:51], v[50:51], v[98:99]
	v_pk_mul_f32 v[48:49], v[48:49], v[112:113]
	v_pk_mul_f32 v[44:45], v[44:45], v[108:109]
	v_pk_mul_f32 v[40:41], v[40:41], v[104:105]
	v_pk_mul_f32 v[36:37], v[36:37], v[100:101]
	v_pk_mul_f32 v[46:47], v[46:47], v[110:111]
	v_pk_mul_f32 v[42:43], v[42:43], v[106:107]
	v_pk_mul_f32 v[38:39], v[38:39], v[102:103]
	v_pk_mul_f32 v[34:35], v[34:35], v[98:99]
	v_pk_mul_f32 v[32:33], v[32:33], v[112:113]
	v_pk_mul_f32 v[28:29], v[28:29], v[108:109]
	v_pk_mul_f32 v[24:25], v[24:25], v[104:105]
	v_pk_mul_f32 v[20:21], v[20:21], v[100:101]
	v_pk_mul_f32 v[30:31], v[30:31], v[110:111]
	v_pk_mul_f32 v[26:27], v[26:27], v[106:107]
	v_pk_mul_f32 v[22:23], v[22:23], v[102:103]
	v_pk_mul_f32 v[18:19], v[18:19], v[98:99]
	v_pk_mul_f32 v[16:17], v[16:17], v[112:113]
	v_pk_mul_f32 v[12:13], v[12:13], v[108:109]
	v_pk_mul_f32 v[8:9], v[8:9], v[104:105]
	v_pk_mul_f32 v[4:5], v[4:5], v[100:101]
	v_pk_mul_f32 v[14:15], v[14:15], v[110:111]
	v_pk_mul_f32 v[10:11], v[10:11], v[106:107]
	v_pk_mul_f32 v[6:7], v[6:7], v[102:103]
	v_pk_mul_f32 v[2:3], v[2:3], v[98:99]
	v_xor_b32_e32 v228, 0x80000000, v236
	v_mov_b32_e32 v229, v228
	v_mov_b64_e32 v[130:131], v[228:229]
	v_mov_b64_e32 v[132:133], v[228:229]
	v_mov_b64_e32 v[134:135], v[228:229]
	v_mov_b64_e32 v[136:137], v[228:229]
	v_mov_b64_e32 v[138:139], v[228:229]
	v_mov_b64_e32 v[140:141], v[228:229]
	v_mov_b64_e32 v[142:143], v[228:229]
	v_mov_b64_e32 v[144:145], v[228:229]

.LBB0_247:
	v_lshl_add_u64 v[98:99], v[220:221], 0, s[12:13]
	v_add_co_u32_e32 v98, vcc, 0x9400000, v98
	s_nop 1
	v_addc_co_u32_e32 v99, vcc, 0, v99, vcc
	global_load_dwordx4 v[166:169], v[98:99], off offset:2048
	global_load_dwordx4 v[170:173], v[98:99], off offset:2176
	v_exp_f32_e32 v114, v114
	v_exp_f32_e32 v115, v115
	s_waitcnt lgkmcnt(6)
	v_mfma_f32_32x32x16_bf16 v[98:113], v[174:177], v[158:161], v[130:145]
	v_add_f32_e32 v224, v224, v114
	v_cvt_pk_bf16_f32 v174, v114, v115
	v_add_f32_e32 v225, v225, v115
	s_waitcnt lgkmcnt(5)
	v_mfma_f32_32x32x16_bf16 v[66:81], v[186:189], v[158:161], v[130:145]
	s_branch .LBB0_228
